# G4: second first-iteration wait also counted to 16 (entry path drains the prologue batch once per phase)
# speedup vs baseline: 1.0236x; 1.0003x over previous
; #define PG8_STAGE(bufoff, gbase, voff) do { _Pragma("unroll") for (int _i = 0; _i < 2; ++_i) \
;         __builtin_amdgcn_global_load_lds((const unsigned*)((const char*)(gbase) + (voff)[_i]), (PG8_LAS unsigned*)(lds + (bufoff) + ldsw + _i * 8192), 16, 0, 0); } while (0)
; #define PG8_WAIT_V(n) asm volatile("s_waitcnt vmcnt(" #n ")" ::: "memory")
; #define PG8_BAR __builtin_amdgcn_s_barrier()
; template <class Epi, class Sched>
; __device__ __forceinline__ void gemm_phase(PG8_LAS unsigned char* lds, const Gemm g, const Sched& S, const Epi& E) {
;     ...
;     for (int i = 0; i < 2; ++i) { int R, C; stage_rc(tid * 16 + i * 8192, R, C); const int Rb = (R & ~31) + perm32(R & 31);
;         voffA[i] = (unsigned)(R * g.lda + C) * 2u; voffB[i] = (unsigned)(Rb * g.ldb + C) * 2u; }
;     const size_t kstep = (size_t)(BK * 2);
;     const size_t hstepA = (size_t)HALF * g.lda * 2, hstepB = (size_t)HALF * g.ldb * 2;
;     const size_t tstepA = 2 * hstepA, tstepB = 2 * hstepB;
;     const unsigned ldsw = (unsigned)wid * 1024u;
;     const int aoff = lds_byte(wr * 64 + fr, fq * 8), boff = lds_byte(wc * 32 + fr, fq * 8);
;     ...
;     PG8_STAGE(PG8_SB(0, 0), cB, voffB); PG8_STAGE(PG8_SB(0, 1), cB + hstepB, voffB); PG8_STAGE(PG8_SA(0, 0), cA, voffA); PG8_STAGE(PG8_SA(0, 1), cA + hstepA, voffA);
;     if (wr == 1) PG8_BAR;
;     PG8_WAIT_V(2); PG8_BAR;
;     PG8_STAGE(PG8_SB(1, 0), cB + kstep, voffB); PG8_STAGE(PG8_SA(1, 0), cA + kstep, voffA); PG8_STAGE(PG8_SB(1, 1), cB + hstepB + kstep, voffB);
;     PG8_WAIT_V(6); PG8_BAR;
.LBB0_572:
	v_lshrrev_b32_e32 v18, 1, v2
	v_and_b32_e32 v18, 24, v18
	v_and_b32_e32 v13, 15, v2
	v_lshlrev_b32_e32 v19, 1, v18
	s_lshl_b32 s0, s0, 5
	v_lshl_or_b32 v1, s11, 6, v13
	v_lshl_or_b32 v19, v13, 6, v19
	v_lshlrev_b32_e32 v13, 2, v13
	s_and_b32 s12, s0, 0x60
	s_waitcnt vmcnt(0)
	v_and_b32_e32 v20, 32, v13
	s_lshl_b32 s1, s11, 13
	s_lshl_b32 s0, s12, 7
	v_readlane_b32 s22, v253, 52
	v_bitop3_b32 v150, v19, s0, v20 bitop3:0xde
	s_add_u32 s0, s24, 0x40080
	v_mov_b32_e32 v135, v0
	v_readlane_b32 s23, v253, 53
	v_bitop3_b32 v21, v19, s1, v20 bitop3:0xde
	s_addc_u32 s1, s25, 0
	s_add_i32 m0, s31, 0x18000
	v_lshl_add_u64 v[4:5], v[4:5], 0, s[78:79]
	v_lshl_add_u64 v[14:15], s[22:23], 0, v[134:135]
	v_mov_b32_e32 v139, v0
	s_waitcnt vmcnt(2)
	s_barrier
	global_load_lds_dwordx4 v[4:5], off
	v_lshl_add_u64 v[4:5], v[6:7], 0, s[78:79]
	s_add_i32 m0, s31, 0x1a000
	s_add_i32 s71, s31, 0x8000
	v_lshl_add_u64 v[16:17], s[22:23], 0, v[138:139]
	global_load_lds_dwordx4 v[4:5], off
	v_lshl_add_u64 v[4:5], v[14:15], 0, s[78:79]
	s_mov_b32 m0, s71
	s_add_i32 s74, s31, 0xa000
	global_load_lds_dwordx4 v[4:5], off
	v_lshl_add_u64 v[4:5], v[16:17], 0, s[78:79]
	s_mov_b32 m0, s74
	v_readlane_b32 s14, v254, 16
	global_load_lds_dwordx4 v[4:5], off
	s_add_i32 m0, s31, 0x1c000
	v_lshl_add_u64 v[4:5], s[0:1], 0, v[136:137]
	global_load_lds_dwordx4 v[4:5], off
	v_lshl_add_u64 v[4:5], s[0:1], 0, v[140:141]
	s_add_i32 m0, s31, 0x1e000
	s_movk_i32 s0, 0xffc0
	global_load_lds_dwordx4 v[4:5], off
	v_mov_b32_e32 v4, s10
	v_bfi_b32 v4, s0, v4, v2
	v_lshlrev_b32_e32 v2, 14, v3
	v_and_b32_e32 v2, 0xffff8000, v2
	v_lshl_add_u32 v2, v8, 11, v2
	v_and_b32_e32 v3, 1, v3
	v_lshl_or_b32 v2, v3, 6, v2
	s_cmpk_lt_u32 s10, 0x100
	v_lshl_add_u32 v144, v9, 1, v2
	v_lshlrev_b32_e32 v2, 14, v10
	s_cselect_b64 s[8:9], -1, 0
	s_lshl_b32 s10, s11, 8
	s_add_i32 s11, 0, 0x22800
	v_and_b32_e32 v2, 0xffff8000, v2
	s_waitcnt vmcnt(6)
	s_add_i32 s10, s11, s10
	v_lshl_add_u32 v2, v11, 11, v2
	v_and_b32_e32 v3, 1, v10
	s_movk_i32 s0, 0x100
	v_ashrrev_i32_e32 v5, 31, v4
	v_readlane_b32 s15, v254, 17
	v_add_u32_e32 v151, s10, v13
	v_lshl_add_u32 v152, v4, 2, s11
	v_lshl_or_b32 v2, v3, 6, v2
	v_readlane_b32 s10, v253, 46
	v_cmp_gt_i32_e64 s[0:1], s0, v4
	v_lshl_add_u64 v[142:143], v[4:5], 4, s[14:15]
	v_or_b32_e32 v153, s12, v18
	v_mov_b32_e32 v145, v0
	v_lshl_add_u32 v146, v12, 1, v2
	v_mov_b32_e32 v147, v0
	s_mov_b32 s82, 0
	v_add_u32_e32 v154, 0, v21
	s_mov_b32 s12, s10
	s_mov_b32 s13, s67
	s_waitcnt vmcnt(0)
	s_barrier
	v_readlane_b32 s11, v253, 47
	s_branch .LBB0_575

; #define PG8_STAGE(bufoff, gbase, voff) do { _Pragma("unroll") for (int _i = 0; _i < 2; ++_i) \
;         __builtin_amdgcn_global_load_lds((const unsigned*)((const char*)(gbase) + (voff)[_i]), (PG8_LAS unsigned*)(lds + (bufoff) + ldsw + _i * 8192), 16, 0, 0); } while (0)
; #define PG8_LDA(dst, b, h) do { _Pragma("unroll") for (int m = 0; m < 4; ++m) _Pragma("unroll") for (int k = 0; k < 2; ++k) dst[m][k] = *(const PG8_LAS bf16x8*)(lds + PG8_SA(b, h) + aoff + m * 2048 + k * 1024); } while (0)
; #define PG8_LDB(dst, b, h) do { _Pragma("unroll") for (int n = 0; n < 2; ++n) _Pragma("unroll") for (int k = 0; k < 2; ++k) dst[n][k] = *(const PG8_LAS bf16x8*)(lds + PG8_SB(b, h) + boff + n * 2048 + k * 1024); } while (0)
; #define PG8_MMA(ai, bj, At, Bt) do { __builtin_amdgcn_s_setprio(1); _Pragma("unroll") for (int m = 0; m < 4; ++m) _Pragma("unroll") for (int n = 0; n < 2; ++n) _Pragma("unroll") for (int k = 0; k < 2; ++k) \
;         acc[ai][bj][m][n] = __builtin_amdgcn_mfma_f32_16x16x32_bf16(Bt[n][k], At[m][k], acc[ai][bj][m][n], 0, 0, 0); __builtin_amdgcn_s_setprio(0); } while (0)
; #define PG8_WAIT_V(n) asm volatile("s_waitcnt vmcnt(" #n ")" ::: "memory")
; #define PG8_WAIT_L(n) asm volatile("s_waitcnt lgkmcnt(" #n ")" ::: "memory")
; #define PG8_BAR __builtin_amdgcn_s_barrier()
; #define PG8_SCHED __builtin_amdgcn_sched_barrier(0)
; template <class Epi, class Sched>
; __device__ __forceinline__ void gemm_phase(PG8_LAS unsigned char* lds, const Gemm g, const Sched& S, const Epi& E) {
;     ...
;         const bool has_next = S.next(ui + 1, nxt);
;         const char* nA = has_next ? (const char*)g.A + (size_t)nxt.pm * tstepA : cA; const char* nB = has_next ? (const char*)g.Bt + (size_t)nxt.pn * tstepB : cB;
;         for (int t = 0; t < nt; t += 2) {
;             const bool last = (t == nt - 2);
;             const char* a1 = cA + (size_t)(t + 1) * kstep;
;             const char* a2 = last ? nA : cA + (size_t)(t + 2) * kstep; const char* b2 = last ? nB : cB + (size_t)(t + 2) * kstep;
;             const char* a3 = a2 + kstep; const char* b3 = b2 + kstep;
;             PG8_LDB(B0, 0, 0); PG8_LDB(B1, 0, 1); PG8_SCHED; PG8_LDA(At, 0, 0); PG8_STAGE(PG8_SA(1, 1), a1 + hstepA, voffA);
;             PG8_WAIT_V(8); PG8_WAIT_L(0); PG8_BAR; PG8_MMA(0, 0, At, B0); PG8_MMA(0, 1, At, B1); PG8_BAR; PG8_SCHED;
.LBB0_580:
	s_ashr_i32 s11, s10, 31
	s_lshl_b64 s[16:17], s[10:11], 19
	s_add_u32 s16, s36, s16
	s_addc_u32 s17, s37, s17
	s_and_b64 s[18:19], s[20:21], exec
	s_cselect_b32 s33, s17, s23
	s_cselect_b32 s46, s16, s22
	s_ashr_i32 s15, s14, 31
	s_lshl_b64 s[18:19], s[14:15], 19
	s_add_u32 s18, s29, s18
	s_addc_u32 s19, s30, s19
	s_and_b64 s[26:27], s[20:21], exec
	s_cselect_b32 s15, s19, s25
	s_cselect_b32 s47, s18, s24
	s_add_u32 s22, s22, 0x40080
	s_addc_u32 s23, s23, 0
	s_add_u32 s48, s24, 0x100
	v_mov_b32_e32 v2, 0
	s_addc_u32 s49, s25, 0
	s_mov_b32 s57, -2
	s_add_u32 s24, s22, 0xfffc0080
	s_addc_u32 s25, s23, -1
	s_add_i32 s58, 0, 0x10000
	s_cmp_eq_u32 s57, 12
	s_cselect_b32 s27, s33, s25
	s_cselect_b32 s26, s46, s24
	v_add_u32_e32 v148, s58, v150
	s_cselect_b32 s25, s15, s49
	s_cselect_b32 s24, s47, s48
	s_add_i32 s64, 0, 0x14000
	ds_read_b128 v[98:101], v148
	ds_read_b128 v[156:159], v148 offset:1024
	ds_read_b128 v[160:163], v148 offset:2048
	ds_read_b128 v[164:167], v148 offset:3072
	v_add_u32_e32 v148, s64, v150
	ds_read_b128 v[168:171], v148
	ds_read_b128 v[172:175], v148 offset:1024
	ds_read_b128 v[176:179], v148 offset:2048
	ds_read_b128 v[180:183], v148 offset:3072
	v_lshl_add_u64 v[148:149], s[22:23], 0, v[144:145]
	s_add_i32 m0, s31, 0xc000
	ds_read_b128 v[184:187], v154
	ds_read_b128 v[188:191], v154 offset:1024
	ds_read_b128 v[192:195], v154 offset:2048
	ds_read_b128 v[196:199], v154 offset:3072
	ds_read_b128 v[200:203], v154 offset:4096
	ds_read_b128 v[204:207], v154 offset:5120
	ds_read_b128 v[208:211], v154 offset:6144
	ds_read_b128 v[214:217], v154 offset:7168
	global_load_lds_dwordx4 v[148:149], off
	v_lshl_add_u64 v[148:149], s[22:23], 0, v[146:147]
	s_add_i32 m0, s31, 0xe000
	s_nop 0
	global_load_lds_dwordx4 v[148:149], off
	s_waitcnt vmcnt(16)
	s_waitcnt lgkmcnt(0)
	s_barrier
	s_setprio 1
	s_waitcnt lgkmcnt(0)
	v_mfma_f32_16x16x32_bf16 v[130:133], v[98:101], v[184:187], 0
	v_mfma_f32_16x16x32_bf16 v[126:129], v[160:163], v[184:187], 0
	v_mfma_f32_16x16x32_bf16 v[114:117], v[98:101], v[192:195], 0
	v_mfma_f32_16x16x32_bf16 v[110:113], v[160:163], v[192:195], 0
	v_mfma_f32_16x16x32_bf16 v[94:97], v[98:101], v[200:203], 0
	v_mfma_f32_16x16x32_bf16 v[90:93], v[160:163], v[200:203], 0
	v_mfma_f32_16x16x32_bf16 v[78:81], v[98:101], v[208:211], 0
	v_mfma_f32_16x16x32_bf16 v[74:77], v[160:163], v[208:211], 0
	v_mfma_f32_16x16x32_bf16 v[130:133], v[156:159], v[188:191], v[130:133]
	v_mfma_f32_16x16x32_bf16 v[126:129], v[164:167], v[188:191], v[126:129]
	v_mfma_f32_16x16x32_bf16 v[114:117], v[156:159], v[196:199], v[114:117]
	v_mfma_f32_16x16x32_bf16 v[110:113], v[164:167], v[196:199], v[110:113]
	v_mfma_f32_16x16x32_bf16 v[94:97], v[156:159], v[204:207], v[94:97]
	v_mfma_f32_16x16x32_bf16 v[90:93], v[164:167], v[204:207], v[90:93]
	v_mfma_f32_16x16x32_bf16 v[78:81], v[156:159], v[214:217], v[78:81]
	v_mfma_f32_16x16x32_bf16 v[74:77], v[164:167], v[214:217], v[74:77]
	s_setprio 0
	s_setprio 1
	v_mfma_f32_16x16x32_bf16 v[122:125], v[168:171], v[184:187], 0
	v_mfma_f32_16x16x32_bf16 v[118:121], v[176:179], v[184:187], 0
	v_mfma_f32_16x16x32_bf16 v[106:109], v[168:171], v[192:195], 0
	v_mfma_f32_16x16x32_bf16 v[102:105], v[176:179], v[192:195], 0
	v_mfma_f32_16x16x32_bf16 v[86:89], v[168:171], v[200:203], 0
	v_mfma_f32_16x16x32_bf16 v[82:85], v[176:179], v[200:203], 0
	v_mfma_f32_16x16x32_bf16 v[70:73], v[168:171], v[208:211], 0
	v_mfma_f32_16x16x32_bf16 v[66:69], v[176:179], v[208:211], 0
	v_mfma_f32_16x16x32_bf16 v[122:125], v[172:175], v[188:191], v[122:125]
	v_mfma_f32_16x16x32_bf16 v[118:121], v[180:183], v[188:191], v[118:121]
	v_mfma_f32_16x16x32_bf16 v[106:109], v[172:175], v[196:199], v[106:109]
	v_mfma_f32_16x16x32_bf16 v[102:105], v[180:183], v[196:199], v[102:105]
	v_mfma_f32_16x16x32_bf16 v[86:89], v[172:175], v[204:207], v[86:89]
	v_mfma_f32_16x16x32_bf16 v[82:85], v[180:183], v[204:207], v[82:85]
	v_mfma_f32_16x16x32_bf16 v[70:73], v[172:175], v[214:217], v[70:73]
	v_mfma_f32_16x16x32_bf16 v[66:69], v[180:183], v[214:217], v[66:69]
	s_setprio 0
	s_barrier
; #define PG8_STAGE(bufoff, gbase, voff) do { _Pragma("unroll") for (int _i = 0; _i < 2; ++_i) \
;         __builtin_amdgcn_global_load_lds((const unsigned*)((const char*)(gbase) + (voff)[_i]), (PG8_LAS unsigned*)(lds + (bufoff) + ldsw + _i * 8192), 16, 0, 0); } while (0)
; #define PG8_LDA(dst, b, h) do { _Pragma("unroll") for (int m = 0; m < 4; ++m) _Pragma("unroll") for (int k = 0; k < 2; ++k) dst[m][k] = *(const PG8_LAS bf16x8*)(lds + PG8_SA(b, h) + aoff + m * 2048 + k * 1024); } while (0)
; #define PG8_MMA(ai, bj, At, Bt) do { __builtin_amdgcn_s_setprio(1); _Pragma("unroll") for (int m = 0; m < 4; ++m) _Pragma("unroll") for (int n = 0; n < 2; ++n) _Pragma("unroll") for (int k = 0; k < 2; ++k) \
;         acc[ai][bj][m][n] = __builtin_amdgcn_mfma_f32_16x16x32_bf16(Bt[n][k], At[m][k], acc[ai][bj][m][n], 0, 0, 0); __builtin_amdgcn_s_setprio(0); } while (0)
; #define PG8_WAIT_V(n) asm volatile("s_waitcnt vmcnt(" #n ")" ::: "memory")
; #define PG8_WAIT_L(n) asm volatile("s_waitcnt lgkmcnt(" #n ")" ::: "memory")
; #define PG8_BAR __builtin_amdgcn_s_barrier()
; #define PG8_SCHED __builtin_amdgcn_sched_barrier(0)
; template <class Epi, class Sched>
; __device__ __forceinline__ void gemm_phase(PG8_LAS unsigned char* lds, const Gemm g, const Sched& S, const Epi& E) {
;     ...
;             PG8_LDA(At, 0, 1); PG8_STAGE(PG8_SB(0, 0), b2, voffB); PG8_STAGE(PG8_SB(0, 1), b2 + hstepB, voffB); PG8_STAGE(PG8_SA(0, 0), a2, voffA);
;             PG8_WAIT_V(8); PG8_WAIT_L(0); PG8_BAR; PG8_MMA(1, 0, At, B0); PG8_MMA(1, 1, At, B1); PG8_BAR; PG8_SCHED;
	s_add_i32 s58, s58, s28
	v_lshl_add_u64 v[148:149], s[24:25], 0, v[136:137]
	s_mov_b32 m0, s58
	ds_read_b128 v[184:187], v154 offset:16384
	ds_read_b128 v[188:191], v154 offset:17408
	ds_read_b128 v[192:195], v154 offset:18432
	ds_read_b128 v[196:199], v154 offset:19456
	ds_read_b128 v[200:203], v154 offset:20480
	ds_read_b128 v[204:207], v154 offset:21504
	ds_read_b128 v[208:211], v154 offset:22528
	ds_read_b128 v[214:217], v154 offset:23552
	global_load_lds_dwordx4 v[148:149], off
	s_add_i32 m0, s58, 0x2000
	s_add_u32 s58, s24, 0x40000
	v_lshl_add_u64 v[212:213], s[24:25], 0, v[140:141]
	s_addc_u32 s59, s25, 0
	s_add_i32 s64, s64, s28
	global_load_lds_dwordx4 v[212:213], off
	v_lshl_add_u64 v[218:219], s[58:59], 0, v[136:137]
	s_mov_b32 m0, s64
	v_lshl_add_u64 v[220:221], s[26:27], 0, v[138:139]
	global_load_lds_dwordx4 v[218:219], off
	v_lshl_add_u64 v[218:219], s[58:59], 0, v[140:141]
	s_add_i32 m0, s64, 0x2000
	s_nop 0
	global_load_lds_dwordx4 v[218:219], off
	v_lshl_add_u64 v[218:219], s[26:27], 0, v[134:135]
	s_mov_b32 m0, s31
	s_nop 0
	global_load_lds_dwordx4 v[218:219], off
	s_mov_b32 m0, s60
	s_nop 0
	global_load_lds_dwordx4 v[220:221], off
	s_waitcnt vmcnt(16)
	s_waitcnt lgkmcnt(0)
	s_barrier
	s_setprio 1
	s_waitcnt lgkmcnt(0)
	v_mfma_f32_16x16x32_bf16 v[62:65], v[98:101], v[184:187], 0
	v_mfma_f32_16x16x32_bf16 v[58:61], v[160:163], v[184:187], 0
	v_mfma_f32_16x16x32_bf16 v[46:49], v[98:101], v[192:195], 0
	v_mfma_f32_16x16x32_bf16 v[42:45], v[160:163], v[192:195], 0
	v_mfma_f32_16x16x32_bf16 v[30:33], v[98:101], v[200:203], 0
	v_mfma_f32_16x16x32_bf16 v[26:29], v[160:163], v[200:203], 0
	v_mfma_f32_16x16x32_bf16 v[14:17], v[98:101], v[208:211], 0
	v_mfma_f32_16x16x32_bf16 v[10:13], v[160:163], v[208:211], 0
	v_mfma_f32_16x16x32_bf16 v[62:65], v[156:159], v[188:191], v[62:65]
	v_mfma_f32_16x16x32_bf16 v[58:61], v[164:167], v[188:191], v[58:61]
	v_mfma_f32_16x16x32_bf16 v[46:49], v[156:159], v[196:199], v[46:49]
	v_mfma_f32_16x16x32_bf16 v[42:45], v[164:167], v[196:199], v[42:45]
	v_mfma_f32_16x16x32_bf16 v[30:33], v[156:159], v[204:207], v[30:33]
	v_mfma_f32_16x16x32_bf16 v[26:29], v[164:167], v[204:207], v[26:29]
	v_mfma_f32_16x16x32_bf16 v[14:17], v[156:159], v[214:217], v[14:17]
	v_mfma_f32_16x16x32_bf16 v[10:13], v[164:167], v[214:217], v[10:13]
	s_setprio 0
	s_setprio 1
	v_mfma_f32_16x16x32_bf16 v[54:57], v[168:171], v[184:187], 0
	v_mfma_f32_16x16x32_bf16 v[50:53], v[176:179], v[184:187], 0
	v_mfma_f32_16x16x32_bf16 v[38:41], v[168:171], v[192:195], 0
	v_mfma_f32_16x16x32_bf16 v[34:37], v[176:179], v[192:195], 0
	v_mfma_f32_16x16x32_bf16 v[22:25], v[168:171], v[200:203], 0
	v_mfma_f32_16x16x32_bf16 v[18:21], v[176:179], v[200:203], 0
	v_mfma_f32_16x16x32_bf16 v[6:9], v[168:171], v[208:211], 0
	v_mfma_f32_16x16x32_bf16 v[2:5], v[176:179], v[208:211], 0
	v_mfma_f32_16x16x32_bf16 v[54:57], v[172:175], v[188:191], v[54:57]
	v_mfma_f32_16x16x32_bf16 v[50:53], v[180:183], v[188:191], v[50:53]
	v_mfma_f32_16x16x32_bf16 v[38:41], v[172:175], v[196:199], v[38:41]
	v_mfma_f32_16x16x32_bf16 v[34:37], v[180:183], v[196:199], v[34:37]
	v_mfma_f32_16x16x32_bf16 v[22:25], v[172:175], v[204:207], v[22:25]
	v_mfma_f32_16x16x32_bf16 v[18:21], v[180:183], v[204:207], v[18:21]
	v_mfma_f32_16x16x32_bf16 v[6:9], v[172:175], v[214:217], v[6:9]
	v_mfma_f32_16x16x32_bf16 v[2:5], v[180:183], v[214:217], v[2:5]
	s_setprio 0
	s_barrier
	s_branch .Lpeel_mid_581
